# prologue mod_item: the 8 w_mod row loads of each k-iteration issued together at the top (were 5 dependent load groups per iteration)
# speedup vs baseline: 1.0163x; 1.0163x over previous
; __device__ __forceinline__ void mod_item(const Params& p, LAS unsigned char* lds, int item, int tid, int wave, int lane) {
;     ...
;     const float* wp = p.in[I_WMOD] + (size_t)l * DM * NMOD + (size_t)(wave * 128) * NMOD + j0 + 4 * lane;
; #pragma unroll 1
;     for (int k8 = 0; k8 < 128; k8 += 8) {
;         f32x4 wv[8];
; #pragma unroll
;         for (int u = 0; u < 8; ++u) wv[u] = *(const f32x4*)(wp + (size_t)(k8 + u) * NMOD);
; #pragma unroll
;         for (int u = 0; u < 8; ++u)
; #pragma unroll
;             for (int r = 0; r < 9; ++r) { const float s = sv[r * 1024 + wave * 128 + k8 + u]; acc[r] += wv[u] * s; }
.LBB0_374:
	global_load_dwordx4 v[170:173], v[80:81], off
	v_add_co_u32_e32 v154, vcc, 0x6000, v80
	s_nop 1
	v_addc_co_u32_e32 v155, vcc, 0, v81, vcc
	global_load_dwordx4 v[174:177], v[154:155], off
	v_add_co_u32_e32 v154, vcc, 0x6000, v154
	s_nop 1
	v_addc_co_u32_e32 v155, vcc, 0, v155, vcc
	global_load_dwordx4 v[178:181], v[154:155], off
	v_add_co_u32_e32 v154, vcc, 0x6000, v154
	s_nop 1
	v_addc_co_u32_e32 v155, vcc, 0, v155, vcc
	global_load_dwordx4 v[182:185], v[154:155], off
	v_add_co_u32_e32 v154, vcc, 0x6000, v154
	s_nop 1
	v_addc_co_u32_e32 v155, vcc, 0, v155, vcc
	global_load_dwordx4 v[186:189], v[154:155], off
	v_add_co_u32_e32 v154, vcc, 0x6000, v154
	s_nop 1
	v_addc_co_u32_e32 v155, vcc, 0, v155, vcc
	global_load_dwordx4 v[190:193], v[154:155], off
	v_add_co_u32_e32 v154, vcc, 0x6000, v154
	s_nop 1
	v_addc_co_u32_e32 v155, vcc, 0, v155, vcc
	global_load_dwordx4 v[194:197], v[154:155], off
	v_add_co_u32_e32 v154, vcc, 0x6000, v154
	s_nop 1
	v_addc_co_u32_e32 v155, vcc, 0, v155, vcc
	global_load_dwordx4 v[198:201], v[154:155], off
	v_mov_b32_e32 v122, s12
	ds_read_b128 v[8:11], v122
	ds_read_b128 v[16:19], v122 offset:16
	ds_read_b128 v[40:43], v122 offset:4096
	ds_read_b128 v[44:47], v122 offset:8192
	ds_read_b128 v[20:23], v122 offset:4112
	ds_read_b128 v[24:27], v122 offset:8208
	s_movk_i32 s13, 0x6000
	s_add_i32 s11, s11, 8
	s_add_i32 s12, s12, 32
	s_mov_b64 s[14:15], 0x30000
	s_cmpk_gt_u32 s11, 0x77
	s_waitcnt vmcnt(7) lgkmcnt(2)
	v_mov_b32_e32 v118, v170
	v_mov_b32_e32 v119, v171
	v_mov_b32_e32 v120, v172
	v_mov_b32_e32 v121, v173
	v_pk_fma_f32 v[90:91], v[120:121], v[44:45], v[30:31] op_sel_hi:[1,0,1]
	v_pk_fma_f32 v[92:93], v[118:119], v[44:45], v[28:29] op_sel_hi:[1,0,1]
	ds_read_b128 v[48:51], v122 offset:12288
	ds_read_b128 v[28:31], v122 offset:12304
	v_pk_fma_f32 v[86:87], v[120:121], v[40:41], v[6:7] op_sel_hi:[1,0,1]
	v_pk_fma_f32 v[88:89], v[118:119], v[40:41], v[4:5] op_sel_hi:[1,0,1]
	v_pk_fma_f32 v[82:83], v[120:121], v[8:9], v[2:3] op_sel_hi:[1,0,1]
	s_waitcnt lgkmcnt(1)
	v_pk_fma_f32 v[94:95], v[120:121], v[48:49], v[34:35] op_sel_hi:[1,0,1]
	v_pk_fma_f32 v[96:97], v[118:119], v[48:49], v[32:33] op_sel_hi:[1,0,1]
	ds_read_b128 v[52:55], v122 offset:16384
	ds_read_b128 v[32:35], v122 offset:16400
	v_pk_fma_f32 v[84:85], v[118:119], v[8:9], v[0:1] op_sel_hi:[1,0,1]
	s_waitcnt lgkmcnt(1)
	v_pk_fma_f32 v[98:99], v[120:121], v[52:53], v[38:39] op_sel_hi:[1,0,1]
	v_pk_fma_f32 v[100:101], v[118:119], v[52:53], v[36:37] op_sel_hi:[1,0,1]
	ds_read_b128 v[56:59], v122 offset:20480
	ds_read_b128 v[36:39], v122 offset:20496
	s_waitcnt lgkmcnt(1)
	v_pk_fma_f32 v[102:103], v[120:121], v[56:57], v[62:63] op_sel_hi:[1,0,1]
	v_pk_fma_f32 v[104:105], v[118:119], v[56:57], v[60:61] op_sel_hi:[1,0,1]
	ds_read_b128 v[60:63], v122 offset:24576
	ds_read_b128 v[12:15], v122 offset:24592
	s_waitcnt lgkmcnt(1)
	v_pk_fma_f32 v[106:107], v[120:121], v[60:61], v[66:67] op_sel_hi:[1,0,1]
	v_pk_fma_f32 v[108:109], v[118:119], v[60:61], v[64:65] op_sel_hi:[1,0,1]
	ds_read_b128 v[64:67], v122 offset:28672
	ds_read_b128 v[4:7], v122 offset:28688
	s_waitcnt lgkmcnt(1)
	v_pk_fma_f32 v[110:111], v[120:121], v[64:65], v[70:71] op_sel_hi:[1,0,1]
	v_pk_fma_f32 v[112:113], v[118:119], v[64:65], v[68:69] op_sel_hi:[1,0,1]
	ds_read_b128 v[68:71], v122 offset:32768
	ds_read_b128 v[0:3], v122 offset:32784
	s_waitcnt lgkmcnt(1)
	v_pk_fma_f32 v[72:73], v[118:119], v[68:69], v[72:73] op_sel_hi:[1,0,1]
	v_add_co_u32_e32 v118, vcc, s13, v80
	s_mov_b32 s13, 0xc000
	s_nop 0
	v_addc_co_u32_e32 v119, vcc, 0, v81, vcc
	v_add_co_u32_e32 v122, vcc, s13, v80
	v_pk_fma_f32 v[74:75], v[120:121], v[68:69], v[74:75] op_sel_hi:[1,0,1]
	s_nop 0
	v_addc_co_u32_e32 v123, vcc, 0, v81, vcc
	s_nop 0
	s_nop 0
	s_nop 0
	s_mov_b32 s13, 0x12000
	s_waitcnt vmcnt(6)
	v_mov_b32_e32 v118, v174
	v_mov_b32_e32 v119, v175
	v_mov_b32_e32 v120, v176
	v_mov_b32_e32 v121, v177
	v_pk_fma_f32 v[82:83], v[120:121], v[8:9], v[82:83] op_sel:[0,1,0]
	v_pk_fma_f32 v[8:9], v[118:119], v[8:9], v[84:85] op_sel:[0,1,0]
	v_pk_fma_f32 v[74:75], v[120:121], v[68:69], v[74:75] op_sel:[0,1,0]
	v_pk_fma_f32 v[68:69], v[118:119], v[68:69], v[72:73] op_sel:[0,1,0]
	s_waitcnt vmcnt(5)
	v_mov_b32_e32 v122, v178
	v_mov_b32_e32 v123, v179
	v_mov_b32_e32 v124, v180
	v_mov_b32_e32 v125, v181
	v_pk_fma_f32 v[72:73], v[124:125], v[10:11], v[82:83] op_sel_hi:[1,0,1]
	v_pk_fma_f32 v[82:83], v[122:123], v[10:11], v[8:9] op_sel_hi:[1,0,1]
	v_add_co_u32_e32 v8, vcc, s13, v80
	v_pk_fma_f32 v[84:85], v[120:121], v[40:41], v[86:87] op_sel:[0,1,0]
	v_pk_fma_f32 v[40:41], v[118:119], v[40:41], v[88:89] op_sel:[0,1,0]
	v_addc_co_u32_e32 v9, vcc, 0, v81, vcc
	s_mov_b32 s13, 0x18000
	v_pk_fma_f32 v[86:87], v[120:121], v[44:45], v[90:91] op_sel:[0,1,0]
	v_pk_fma_f32 v[90:91], v[120:121], v[52:53], v[98:99] op_sel:[0,1,0]
	v_pk_fma_f32 v[98:99], v[122:123], v[42:43], v[40:41] op_sel_hi:[1,0,1]
	v_add_co_u32_e32 v40, vcc, s13, v80
	v_pk_fma_f32 v[44:45], v[118:119], v[44:45], v[92:93] op_sel:[0,1,0]
	v_pk_fma_f32 v[88:89], v[120:121], v[48:49], v[94:95] op_sel:[0,1,0]
	v_pk_fma_f32 v[48:49], v[118:119], v[48:49], v[96:97] op_sel:[0,1,0]
	v_addc_co_u32_e32 v41, vcc, 0, v81, vcc
	v_pk_fma_f32 v[84:85], v[124:125], v[42:43], v[84:85] op_sel_hi:[1,0,1]
	v_pk_fma_f32 v[86:87], v[124:125], v[46:47], v[86:87] op_sel_hi:[1,0,1]
	v_pk_fma_f32 v[44:45], v[122:123], v[46:47], v[44:45] op_sel_hi:[1,0,1]
	v_pk_fma_f32 v[88:89], v[124:125], v[50:51], v[88:89] op_sel_hi:[1,0,1]
	v_pk_fma_f32 v[48:49], v[122:123], v[50:51], v[48:49] op_sel_hi:[1,0,1]
	v_mov_b32_e32 v46, v11
	v_mov_b32_e32 v50, v43
	s_nop 0
	s_nop 0
	s_nop 0
; __device__ __forceinline__ void mod_item(const Params& p, LAS unsigned char* lds, int item, int tid, int wave, int lane) {
;     ...
;         for (int u = 0; u < 8; ++u) wv[u] = *(const f32x4*)(wp + (size_t)(k8 + u) * NMOD);
; #pragma unroll
;         for (int u = 0; u < 8; ++u)
; #pragma unroll
;             for (int r = 0; r < 9; ++r) { const float s = sv[r * 1024 + wave * 128 + k8 + u]; acc[r] += wv[u] * s; }
	v_pk_fma_f32 v[52:53], v[118:119], v[52:53], v[100:101] op_sel:[0,1,0]
	v_pk_fma_f32 v[92:93], v[120:121], v[56:57], v[102:103] op_sel:[0,1,0]
	v_pk_fma_f32 v[56:57], v[118:119], v[56:57], v[104:105] op_sel:[0,1,0]
	v_pk_fma_f32 v[94:95], v[120:121], v[60:61], v[106:107] op_sel:[0,1,0]
	v_pk_fma_f32 v[60:61], v[118:119], v[60:61], v[108:109] op_sel:[0,1,0]
	v_pk_fma_f32 v[96:97], v[120:121], v[64:65], v[110:111] op_sel:[0,1,0]
	v_pk_fma_f32 v[64:65], v[118:119], v[64:65], v[112:113] op_sel:[0,1,0]
	v_pk_fma_f32 v[90:91], v[124:125], v[54:55], v[90:91] op_sel_hi:[1,0,1]
	v_pk_fma_f32 v[52:53], v[122:123], v[54:55], v[52:53] op_sel_hi:[1,0,1]
	v_pk_fma_f32 v[92:93], v[124:125], v[58:59], v[92:93] op_sel_hi:[1,0,1]
	v_pk_fma_f32 v[56:57], v[122:123], v[58:59], v[56:57] op_sel_hi:[1,0,1]
	v_pk_fma_f32 v[94:95], v[124:125], v[62:63], v[94:95] op_sel_hi:[1,0,1]
	v_pk_fma_f32 v[60:61], v[122:123], v[62:63], v[60:61] op_sel_hi:[1,0,1]
	v_pk_fma_f32 v[96:97], v[124:125], v[66:67], v[96:97] op_sel_hi:[1,0,1]
	v_pk_fma_f32 v[64:65], v[122:123], v[66:67], v[64:65] op_sel_hi:[1,0,1]
	v_pk_fma_f32 v[74:75], v[124:125], v[70:71], v[74:75] op_sel_hi:[1,0,1]
	v_pk_fma_f32 v[68:69], v[122:123], v[70:71], v[68:69] op_sel_hi:[1,0,1]
	v_mov_b32_e32 v54, v47
	v_mov_b32_e32 v58, v51
	v_mov_b32_e32 v62, v55
	v_mov_b32_e32 v66, v59
	v_mov_b32_e32 v70, v63
	v_mov_b32_e32 v100, v67
	v_mov_b32_e32 v102, v71
	s_mov_b32 s13, 0x1e000
	s_waitcnt vmcnt(4)
	v_mov_b32_e32 v8, v182
	v_mov_b32_e32 v9, v183
	v_mov_b32_e32 v10, v184
	v_mov_b32_e32 v11, v185
	v_pk_fma_f32 v[72:73], v[10:11], v[46:47], v[72:73] op_sel_hi:[1,0,1]
	v_pk_fma_f32 v[46:47], v[8:9], v[46:47], v[82:83] op_sel_hi:[1,0,1]
	v_pk_fma_f32 v[82:83], v[10:11], v[50:51], v[84:85] op_sel_hi:[1,0,1]
	v_pk_fma_f32 v[50:51], v[8:9], v[50:51], v[98:99] op_sel_hi:[1,0,1]
	v_pk_fma_f32 v[84:85], v[10:11], v[54:55], v[86:87] op_sel_hi:[1,0,1]
	v_pk_fma_f32 v[44:45], v[8:9], v[54:55], v[44:45] op_sel_hi:[1,0,1]
	v_pk_fma_f32 v[48:49], v[8:9], v[58:59], v[48:49] op_sel_hi:[1,0,1]
	v_pk_fma_f32 v[52:53], v[8:9], v[62:63], v[52:53] op_sel_hi:[1,0,1]
	v_pk_fma_f32 v[56:57], v[8:9], v[66:67], v[56:57] op_sel_hi:[1,0,1]
	v_pk_fma_f32 v[60:61], v[8:9], v[70:71], v[60:61] op_sel_hi:[1,0,1]
	v_pk_fma_f32 v[64:65], v[8:9], v[100:101], v[64:65] op_sel_hi:[1,0,1]
	v_pk_fma_f32 v[8:9], v[8:9], v[102:103], v[68:69] op_sel_hi:[1,0,1]
	v_pk_fma_f32 v[54:55], v[10:11], v[58:59], v[88:89] op_sel_hi:[1,0,1]
	v_pk_fma_f32 v[58:59], v[10:11], v[62:63], v[90:91] op_sel_hi:[1,0,1]
	v_pk_fma_f32 v[62:63], v[10:11], v[66:67], v[92:93] op_sel_hi:[1,0,1]
	v_pk_fma_f32 v[66:67], v[10:11], v[70:71], v[94:95] op_sel_hi:[1,0,1]
	v_pk_fma_f32 v[70:71], v[10:11], v[100:101], v[96:97] op_sel_hi:[1,0,1]
	v_pk_fma_f32 v[10:11], v[10:11], v[102:103], v[74:75] op_sel_hi:[1,0,1]
	s_waitcnt vmcnt(3)
	v_mov_b32_e32 v40, v186
	v_mov_b32_e32 v41, v187
	v_mov_b32_e32 v42, v188
	v_mov_b32_e32 v43, v189
	v_pk_fma_f32 v[74:75], v[42:43], v[24:25], v[84:85] op_sel_hi:[1,0,1]
	s_waitcnt lgkmcnt(0)
	v_pk_fma_f32 v[84:85], v[40:41], v[0:1], v[8:9] op_sel_hi:[1,0,1]
	v_add_co_u32_e32 v8, vcc, s13, v80
	s_mov_b32 s13, 0x24000
	s_nop 0
	v_addc_co_u32_e32 v9, vcc, 0, v81, vcc
	v_pk_fma_f32 v[68:69], v[42:43], v[16:17], v[72:73] op_sel_hi:[1,0,1]
	v_pk_fma_f32 v[72:73], v[42:43], v[20:21], v[82:83] op_sel_hi:[1,0,1]
	v_pk_fma_f32 v[82:83], v[42:43], v[0:1], v[10:11] op_sel_hi:[1,0,1]
	v_add_co_u32_e32 v10, vcc, s13, v80
	v_pk_fma_f32 v[46:47], v[40:41], v[16:17], v[46:47] op_sel_hi:[1,0,1]
	s_nop 0
	v_addc_co_u32_e32 v11, vcc, 0, v81, vcc
	v_pk_fma_f32 v[50:51], v[40:41], v[20:21], v[50:51] op_sel_hi:[1,0,1]
	v_pk_fma_f32 v[44:45], v[40:41], v[24:25], v[44:45] op_sel_hi:[1,0,1]
	v_pk_fma_f32 v[54:55], v[42:43], v[28:29], v[54:55] op_sel_hi:[1,0,1]
	v_pk_fma_f32 v[48:49], v[40:41], v[28:29], v[48:49] op_sel_hi:[1,0,1]
	v_pk_fma_f32 v[58:59], v[42:43], v[32:33], v[58:59] op_sel_hi:[1,0,1]
	v_pk_fma_f32 v[52:53], v[40:41], v[32:33], v[52:53] op_sel_hi:[1,0,1]
	v_pk_fma_f32 v[62:63], v[42:43], v[36:37], v[62:63] op_sel_hi:[1,0,1]
	v_pk_fma_f32 v[56:57], v[40:41], v[36:37], v[56:57] op_sel_hi:[1,0,1]
	v_pk_fma_f32 v[66:67], v[42:43], v[12:13], v[66:67] op_sel_hi:[1,0,1]
	v_pk_fma_f32 v[60:61], v[40:41], v[12:13], v[60:61] op_sel_hi:[1,0,1]
	v_pk_fma_f32 v[70:71], v[42:43], v[4:5], v[70:71] op_sel_hi:[1,0,1]
	v_pk_fma_f32 v[64:65], v[40:41], v[4:5], v[64:65] op_sel_hi:[1,0,1]
	s_nop 0
	s_nop 0
	s_nop 0
	s_mov_b32 s13, 0x2a000
	s_waitcnt vmcnt(2)
; #define LAS __attribute__((address_space(3)))
; __device__ __forceinline__ void mod_item(const Params& p, LAS unsigned char* lds, int item, int tid, int wave, int lane) {
;     ...
;         for (int u = 0; u < 8; ++u) wv[u] = *(const f32x4*)(wp + (size_t)(k8 + u) * NMOD);
; #pragma unroll
;         for (int u = 0; u < 8; ++u)
; #pragma unroll
;             for (int r = 0; r < 9; ++r) { const float s = sv[r * 1024 + wave * 128 + k8 + u]; acc[r] += wv[u] * s; }
;     }
; #pragma unroll
;     for (int r = 0; r < 9; ++r) *(LAS f32x4*)(part + (wave * 9 + r) * 256 + 4 * lane) = acc[r];
;     __syncthreads();
;     float* mod = (float*)(p.ws + WS_MOD) + (size_t)l * 9 * NMOD;
;     for (int i = tid; i < 9 * 256; i += NTHR) { const int r = i >> 8, j = i & 255; float s = p.in[I_BMOD][l * NMOD + j0 + j];
	v_mov_b32_e32 v40, v190
	v_mov_b32_e32 v41, v191
	v_mov_b32_e32 v42, v192
	v_mov_b32_e32 v43, v193
	v_pk_fma_f32 v[68:69], v[42:43], v[16:17], v[68:69] op_sel:[0,1,0]
	v_pk_fma_f32 v[46:47], v[40:41], v[16:17], v[46:47] op_sel:[0,1,0]
	v_pk_fma_f32 v[72:73], v[42:43], v[20:21], v[72:73] op_sel:[0,1,0]
	v_pk_fma_f32 v[50:51], v[40:41], v[20:21], v[50:51] op_sel:[0,1,0]
	v_pk_fma_f32 v[74:75], v[42:43], v[24:25], v[74:75] op_sel:[0,1,0]
	v_pk_fma_f32 v[44:45], v[40:41], v[24:25], v[44:45] op_sel:[0,1,0]
	v_pk_fma_f32 v[54:55], v[42:43], v[28:29], v[54:55] op_sel:[0,1,0]
	v_pk_fma_f32 v[48:49], v[40:41], v[28:29], v[48:49] op_sel:[0,1,0]
	v_pk_fma_f32 v[58:59], v[42:43], v[32:33], v[58:59] op_sel:[0,1,0]
	v_pk_fma_f32 v[52:53], v[40:41], v[32:33], v[52:53] op_sel:[0,1,0]
	v_pk_fma_f32 v[86:87], v[42:43], v[36:37], v[62:63] op_sel:[0,1,0]
	v_pk_fma_f32 v[56:57], v[40:41], v[36:37], v[56:57] op_sel:[0,1,0]
	v_pk_fma_f32 v[66:67], v[42:43], v[12:13], v[66:67] op_sel:[0,1,0]
	v_pk_fma_f32 v[12:13], v[40:41], v[12:13], v[60:61] op_sel:[0,1,0]
	v_pk_fma_f32 v[60:61], v[42:43], v[4:5], v[70:71] op_sel:[0,1,0]
	v_pk_fma_f32 v[62:63], v[40:41], v[4:5], v[64:65] op_sel:[0,1,0]
	v_pk_fma_f32 v[4:5], v[42:43], v[0:1], v[82:83] op_sel:[0,1,0]
	v_pk_fma_f32 v[0:1], v[40:41], v[0:1], v[84:85] op_sel:[0,1,0]
	s_waitcnt vmcnt(1)
	v_mov_b32_e32 v8, v194
	v_mov_b32_e32 v9, v195
	v_mov_b32_e32 v10, v196
	v_mov_b32_e32 v11, v197
	v_pk_fma_f32 v[16:17], v[10:11], v[18:19], v[68:69] op_sel_hi:[1,0,1]
	v_pk_fma_f32 v[20:21], v[8:9], v[18:19], v[46:47] op_sel_hi:[1,0,1]
	v_mov_b32_e32 v28, v19
	v_pk_fma_f32 v[18:19], v[10:11], v[22:23], v[72:73] op_sel_hi:[1,0,1]
	v_pk_fma_f32 v[24:25], v[8:9], v[22:23], v[50:51] op_sel_hi:[1,0,1]
	v_mov_b32_e32 v36, v23
	v_pk_fma_f32 v[22:23], v[10:11], v[26:27], v[74:75] op_sel_hi:[1,0,1]
	v_pk_fma_f32 v[32:33], v[8:9], v[26:27], v[44:45] op_sel_hi:[1,0,1]
	v_mov_b32_e32 v42, v27
	v_pk_fma_f32 v[26:27], v[10:11], v[30:31], v[54:55] op_sel_hi:[1,0,1]
	v_pk_fma_f32 v[40:41], v[8:9], v[30:31], v[48:49] op_sel_hi:[1,0,1]
	v_add_co_u32_e32 v30, vcc, s13, v80
	v_mov_b32_e32 v48, v31
	s_nop 0
	v_addc_co_u32_e32 v31, vcc, 0, v81, vcc
	v_pk_fma_f32 v[44:45], v[10:11], v[34:35], v[58:59] op_sel_hi:[1,0,1]
	v_pk_fma_f32 v[58:59], v[10:11], v[14:15], v[66:67] op_sel_hi:[1,0,1]
	v_pk_fma_f32 v[64:65], v[8:9], v[14:15], v[12:13] op_sel_hi:[1,0,1]
	v_mov_b32_e32 v68, v15
	s_nop 0
	v_pk_fma_f32 v[46:47], v[8:9], v[34:35], v[52:53] op_sel_hi:[1,0,1]
	v_mov_b32_e32 v54, v35
	v_pk_fma_f32 v[50:51], v[10:11], v[38:39], v[86:87] op_sel_hi:[1,0,1]
	v_pk_fma_f32 v[52:53], v[8:9], v[38:39], v[56:57] op_sel_hi:[1,0,1]
	v_mov_b32_e32 v56, v39
	v_pk_fma_f32 v[70:71], v[10:11], v[6:7], v[60:61] op_sel_hi:[1,0,1]
	v_pk_fma_f32 v[72:73], v[8:9], v[6:7], v[62:63] op_sel_hi:[1,0,1]
	v_mov_b32_e32 v74, v7
	v_mov_b32_e32 v82, v3
	v_pk_fma_f32 v[10:11], v[10:11], v[2:3], v[4:5] op_sel_hi:[1,0,1]
	v_pk_fma_f32 v[8:9], v[8:9], v[2:3], v[0:1] op_sel_hi:[1,0,1]
	v_lshl_add_u64 v[80:81], v[80:81], 0, s[14:15]
	s_waitcnt vmcnt(0)
	v_mov_b32_e32 v12, v198
	v_mov_b32_e32 v13, v199
	v_mov_b32_e32 v14, v200
	v_mov_b32_e32 v15, v201
	v_pk_fma_f32 v[2:3], v[14:15], v[28:29], v[16:17] op_sel_hi:[1,0,1]
	v_pk_fma_f32 v[0:1], v[12:13], v[28:29], v[20:21] op_sel_hi:[1,0,1]
	v_pk_fma_f32 v[6:7], v[14:15], v[36:37], v[18:19] op_sel_hi:[1,0,1]
	v_pk_fma_f32 v[4:5], v[12:13], v[36:37], v[24:25] op_sel_hi:[1,0,1]
	v_pk_fma_f32 v[30:31], v[14:15], v[42:43], v[22:23] op_sel_hi:[1,0,1]
	v_pk_fma_f32 v[28:29], v[12:13], v[42:43], v[32:33] op_sel_hi:[1,0,1]
	v_pk_fma_f32 v[34:35], v[14:15], v[48:49], v[26:27] op_sel_hi:[1,0,1]
	v_pk_fma_f32 v[32:33], v[12:13], v[48:49], v[40:41] op_sel_hi:[1,0,1]
	v_pk_fma_f32 v[38:39], v[14:15], v[54:55], v[44:45] op_sel_hi:[1,0,1]
	v_pk_fma_f32 v[36:37], v[12:13], v[54:55], v[46:47] op_sel_hi:[1,0,1]
	v_pk_fma_f32 v[62:63], v[14:15], v[56:57], v[50:51] op_sel_hi:[1,0,1]
	v_pk_fma_f32 v[60:61], v[12:13], v[56:57], v[52:53] op_sel_hi:[1,0,1]
	v_pk_fma_f32 v[66:67], v[14:15], v[68:69], v[58:59] op_sel_hi:[1,0,1]
	v_pk_fma_f32 v[64:65], v[12:13], v[68:69], v[64:65] op_sel_hi:[1,0,1]
	v_pk_fma_f32 v[70:71], v[14:15], v[74:75], v[70:71] op_sel_hi:[1,0,1]
	v_pk_fma_f32 v[68:69], v[12:13], v[74:75], v[72:73] op_sel_hi:[1,0,1]
	v_pk_fma_f32 v[74:75], v[14:15], v[82:83], v[10:11] op_sel_hi:[1,0,1]
	v_pk_fma_f32 v[72:73], v[12:13], v[82:83], v[8:9] op_sel_hi:[1,0,1]
	s_cbranch_scc0 .LBB0_374
	ds_write_b128 v117, v[0:3] offset:36864
	ds_write_b128 v117, v[4:7] offset:37888
	ds_write_b128 v117, v[28:31] offset:38912
	ds_write_b128 v117, v[32:35] offset:39936
	ds_write_b128 v117, v[36:39] offset:40960
	ds_write_b128 v117, v[60:63] offset:41984
	ds_write_b128 v117, v[64:67] offset:43008
	ds_write_b128 v117, v[68:71] offset:44032
	ds_write_b128 v117, v[72:75] offset:45056
	s_waitcnt lgkmcnt(0)
	s_barrier
	s_and_saveexec_b64 s[12:13], s[6:7]
	s_cbranch_execz .LBB0_369
	s_mul_i32 s14, s18, 0x36000
	s_mul_hi_i32 s11, s18, 0x36000
	s_add_u32 s14, s73, s14
	s_addc_u32 s15, s57, s11
	s_mul_i32 s11, s18, 0x1800
	s_add_i32 s11, s11, s10
	v_or_b32_e32 v0, s11, v114
	v_ashrrev_i32_e32 v1, 31, v0
	v_lshl_add_u64 v[0:1], v[0:1], 2, s[8:9]
	v_or_b32_e32 v2, s10, v114
	s_mov_b64 s[10:11], 0
	v_mov_b32_e32 v3, v166
